# MLA unmasked-tile fast path: S0/S1 chained QK with softmax interleaved in MFMA gaps, deferred row sums, K-fragment prefetch, mid-tile pair barrier
# speedup vs baseline: 1.0254x; 1.0254x over previous
.LBB0_476:
	s_waitcnt vmcnt(0)
	v_lshlrev_b32_e32 v28, 16, v8
	v_and_b32_e32 v29, 0xffff0000, v8
	v_mov_b32_e32 v31, v26
	v_mov_b32_e32 v26, v25
	v_lshlrev_b32_e32 v6, 16, v12
	v_and_b32_e32 v7, 0xffff0000, v12
	v_mov_b32_e32 v30, v24
	v_pk_mul_f32 v[24:25], v[26:27], v[28:29]
	v_lshlrev_b32_e32 v8, 16, v9
	v_pk_fma_f32 v[24:25], v[30:31], v[6:7], v[24:25] neg_lo:[0,0,1] neg_hi:[0,0,1]
	v_and_b32_e32 v9, 0xffff0000, v9
	v_cvt_pk_bf16_f32 v90, v24, v25
	v_pk_mul_f32 v[24:25], v[30:31], v[28:29]
	v_mov_b32_e32 v12, v20
	v_pk_fma_f32 v[6:7], v[26:27], v[6:7], v[24:25]
	v_lshlrev_b32_e32 v133, 2, v38
	v_cvt_pk_bf16_f32 v94, v6, v7
	v_lshlrev_b32_e32 v6, 16, v13
	v_and_b32_e32 v7, 0xffff0000, v13
	v_mov_b32_e32 v13, v22
	v_mov_b32_e32 v22, v21
	v_pk_mul_f32 v[20:21], v[22:23], v[8:9]
	v_pk_mul_f32 v[8:9], v[12:13], v[8:9]
	v_pk_fma_f32 v[20:21], v[12:13], v[6:7], v[20:21] neg_lo:[0,0,1] neg_hi:[0,0,1]
	v_pk_fma_f32 v[6:7], v[22:23], v[6:7], v[8:9]
	v_lshlrev_b32_e32 v8, 16, v10
	v_and_b32_e32 v9, 0xffff0000, v10
	v_mov_b32_e32 v12, v16
	v_mov_b32_e32 v13, v18
	v_mov_b32_e32 v18, v17
	v_cvt_pk_bf16_f32 v95, v6, v7
	v_lshlrev_b32_e32 v6, 16, v14
	v_and_b32_e32 v7, 0xffff0000, v14
	v_pk_mul_f32 v[16:17], v[18:19], v[8:9]
	v_pk_mul_f32 v[8:9], v[12:13], v[8:9]
	v_pk_fma_f32 v[16:17], v[12:13], v[6:7], v[16:17] neg_lo:[0,0,1] neg_hi:[0,0,1]
	v_pk_fma_f32 v[6:7], v[18:19], v[6:7], v[8:9]
	v_lshlrev_b32_e32 v8, 16, v11
	v_and_b32_e32 v9, 0xffff0000, v11
	v_mov_b32_e32 v11, v4
	v_mov_b32_e32 v4, v3
	v_cvt_pk_bf16_f32 v96, v6, v7
	v_lshlrev_b32_e32 v6, 16, v15
	v_and_b32_e32 v7, 0xffff0000, v15
	v_mov_b32_e32 v10, v2
	v_pk_mul_f32 v[2:3], v[4:5], v[8:9]
	v_lshrrev_b32_e32 v0, 2, v37
	v_pk_fma_f32 v[2:3], v[10:11], v[6:7], v[2:3] neg_lo:[0,0,1] neg_hi:[0,0,1]
	v_and_or_b32 v0, v0, 3, v133
	v_cvt_pk_bf16_f32 v93, v2, v3
	v_pk_mul_f32 v[2:3], v[10:11], v[8:9]
	v_mul_u32_u24_e32 v144, 0xc0, v0
	v_pk_fma_f32 v[2:3], v[4:5], v[6:7], v[2:3]
	v_and_b32_e32 v0, 16, v37
	v_cvt_pk_bf16_f32 v97, v2, v3
	v_lshlrev_b32_e32 v2, 2, v37
	s_lshr_b32 s13, s30, 6
	v_and_or_b32 v0, v2, 12, v0
	s_add_i32 s30, s30, s31
	v_lshlrev_b32_e32 v145, 1, v0
	v_add_u32_e32 v0, s30, v36
	v_mov_b32_e32 v14, v1
	v_mov_b32_e32 v15, v1
	v_cvt_pk_bf16_f32 v91, v20, v21
	s_waitcnt vmcnt(0)
	v_sub_u32_e32 v146, v0, v133
	v_mov_b32_e32 v0, v1
	v_mov_b32_e32 v2, v1
	v_mov_b32_e32 v3, v1
	v_mov_b32_e32 v4, v1
	v_mov_b32_e32 v5, v1
	v_mov_b32_e32 v6, v1
	v_mov_b32_e32 v7, v1
	v_mov_b32_e32 v8, v1
	v_mov_b32_e32 v9, v1
	v_mov_b32_e32 v10, v1
	v_mov_b32_e32 v11, v1
	v_mov_b32_e32 v12, v1
	v_mov_b32_e32 v13, v1
	v_mov_b64_e32 v[32:33], v[14:15]
	v_cvt_pk_bf16_f32 v92, v16, v17
	v_mov_b64_e32 v[30:31], v[12:13]
	v_mov_b64_e32 v[28:29], v[10:11]
	v_mov_b64_e32 v[26:27], v[8:9]
	v_mov_b64_e32 v[24:25], v[6:7]
	v_mov_b64_e32 v[22:23], v[4:5]
	v_mov_b64_e32 v[20:21], v[2:3]
	v_mov_b64_e32 v[18:19], v[0:1]
	v_mov_b64_e32 v[16:17], v[14:15]
	s_or_b32 s7, s4, 31
	s_or_b32 s14, s13, 3
	v_mul_u32_u24_e32 v143, 0xd0, v36
	s_add_i32 s20, s13, 4
	s_mov_b32 s30, 0
	v_mov_b32_e32 v148, 0xefa18f08
	v_mov_b32_e32 v147, 0
	s_mov_b32 s31, 63
	s_mov_b32 s42, 0
	v_mov_b64_e32 v[202:203], 0
	v_mov_b64_e32 v[204:205], 0
	v_mov_b64_e32 v[206:207], 0
	v_mov_b64_e32 v[208:209], 0
	v_mov_b64_e32 v[210:211], 0
	v_mov_b64_e32 v[212:213], 0
	v_mov_b64_e32 v[214:215], 0
	v_mov_b64_e32 v[216:217], 0
	v_mov_b64_e32 v[218:219], 0
	v_mov_b64_e32 v[220:221], 0
	v_mov_b64_e32 v[222:223], 0
	v_mov_b64_e32 v[224:225], 0
	v_mov_b64_e32 v[226:227], 0
	v_mov_b64_e32 v[228:229], 0
	v_mov_b64_e32 v[230:231], 0
	v_mov_b64_e32 v[232:233], 0
	v_mov_b64_e32 v[14:15], v[12:13]
	v_mov_b64_e32 v[12:13], v[10:11]
	v_mov_b64_e32 v[10:11], v[8:9]
	v_mov_b64_e32 v[8:9], v[6:7]
	v_mov_b64_e32 v[6:7], v[4:5]
	v_mov_b64_e32 v[4:5], v[2:3]
	v_mov_b64_e32 v[2:3], v[0:1]
	s_waitcnt lgkmcnt(0)
	s_barrier
	s_branch .LBB0_478

.LBB0_485:
	s_andn2_b64 vcc, exec, s[40:41]
	s_cbranch_vccnz .LBB0_498
	s_cmp_le_u32 s31, s4
	s_cbranch_scc1 .Lmla_fast
	v_add_f32_e32 v254, v202, v203
	v_add_f32_e32 v255, v204, v205
	v_add_f32_e32 v254, v254, v206
	v_add_f32_e32 v255, v255, v207
	v_add_f32_e32 v254, v254, v208
	v_add_f32_e32 v255, v255, v209
	v_add_f32_e32 v254, v254, v210
	v_add_f32_e32 v255, v255, v211
	v_add_f32_e32 v254, v254, v212
	v_add_f32_e32 v255, v255, v213
	v_add_f32_e32 v254, v254, v214
	v_add_f32_e32 v255, v255, v215
	v_add_f32_e32 v254, v254, v216
	v_add_f32_e32 v255, v255, v217
	v_add_f32_e32 v254, v254, v218
	v_add_f32_e32 v255, v255, v219
	v_add_f32_e32 v254, v254, v220
	v_add_f32_e32 v255, v255, v221
	v_add_f32_e32 v254, v254, v222
	v_add_f32_e32 v255, v255, v223
	v_add_f32_e32 v254, v254, v224
	v_add_f32_e32 v255, v255, v225
	v_add_f32_e32 v254, v254, v226
	v_add_f32_e32 v255, v255, v227
	v_add_f32_e32 v254, v254, v228
	v_add_f32_e32 v255, v255, v229
	v_add_f32_e32 v254, v254, v230
	v_add_f32_e32 v255, v255, v231
	v_add_f32_e32 v254, v254, v232
	v_add_f32_e32 v255, v255, v233
	v_add_f32_e32 v254, v254, v255
	v_add_f32_e32 v147, v147, v254
	s_and_b32 s8, s30, 3
	s_mulk_i32 s8, 0x6400
	s_add_i32 s8, s8, 0
	v_add3_u32 v0, s8, v143, v132
	ds_read_b128 v[34:37], v0
	ds_read_b128 v[150:153], v0 offset:32
	ds_read_b128 v[38:41], v0 offset:6656
	ds_read_b128 v[154:157], v0 offset:6688
	ds_read_b128 v[158:161], v0 offset:64
	ds_read_b128 v[162:165], v0 offset:96
	ds_read_b128 v[166:169], v0 offset:6720
	ds_read_b128 v[170:173], v0 offset:6752
	ds_read_b128 v[174:177], v0 offset:128
	ds_read_b128 v[178:181], v0 offset:160
	ds_read_b128 v[194:197], v0 offset:6784
	ds_read_b128 v[198:201], v0 offset:6816
	v_add3_u32 v0, s8, v144, v145
	ds_read_b64_tr_b16 v[126:127], v0 offset:13312
	ds_read_b64_tr_b16 v[128:129], v0 offset:14848
	ds_read_b64_tr_b16 v[124:125], v0 offset:14912
	ds_read_b64_tr_b16 v[122:123], v0 offset:13376
	ds_read_b64_tr_b16 v[118:119], v0 offset:16384
	ds_read_b64_tr_b16 v[120:121], v0 offset:17920
	ds_read_b64_tr_b16 v[116:117], v0 offset:17984
	ds_read_b64_tr_b16 v[114:115], v0 offset:16448
	ds_read_b64_tr_b16 v[110:111], v0 offset:19456
	ds_read_b64_tr_b16 v[112:113], v0 offset:20992
	ds_read_b64_tr_b16 v[108:109], v0 offset:21056
	ds_read_b64_tr_b16 v[106:107], v0 offset:19520
	ds_read_b64_tr_b16 v[102:103], v0 offset:22528
	ds_read_b64_tr_b16 v[104:105], v0 offset:24064
	ds_read_b64_tr_b16 v[100:101], v0 offset:24128
	ds_read_b64_tr_b16 v[98:99], v0 offset:22592
	s_waitcnt lgkmcnt(0)
	v_mfma_f32_32x32x16_bf16 v[50:65], v[34:37], v[74:77], 0
	v_mfma_f32_32x32x16_bf16 v[34:49], v[38:41], v[74:77], 0
	v_mfma_f32_32x32x16_bf16 v[50:65], v[150:153], v[78:81], v[50:65]
	v_mfma_f32_32x32x16_bf16 v[34:49], v[154:157], v[78:81], v[34:49]
	v_mfma_f32_32x32x16_bf16 v[50:65], v[158:161], v[82:85], v[50:65]
	v_mfma_f32_32x32x16_bf16 v[34:49], v[166:169], v[82:85], v[34:49]
	v_mfma_f32_32x32x16_bf16 v[50:65], v[162:165], v[86:89], v[50:65]
	v_mfma_f32_32x32x16_bf16 v[34:49], v[170:173], v[86:89], v[34:49]
	v_mfma_f32_32x32x16_bf16 v[50:65], v[174:177], v[90:93], v[50:65]
	v_mfma_f32_32x32x16_bf16 v[34:49], v[194:197], v[90:93], v[34:49]
	v_mfma_f32_32x32x16_bf16 v[50:65], v[178:181], v[94:97], v[50:65]
	v_mfma_f32_32x32x16_bf16 v[34:49], v[198:201], v[94:97], v[34:49]
	s_andn2_b64 vcc, exec, s[38:39]
	s_cbranch_vccnz .LBB0_493
	s_add_i32 s34, s30, 2
	s_cmp_gt_u32 s34, s14
	s_cbranch_scc1 .LBB0_490
	s_and_b32 s8, s34, 2
	s_mulk_i32 s8, 0x6400
	s_add_i32 s34, s8, 0
	s_add_i32 s8, s34, s5
	s_mov_b32 m0, s8
	s_and_b64 vcc, exec, s[36:37]
	global_load_lds_dwordx4 v[66:67], off
	s_add_i32 m0, s8, 0x2000
	v_lshl_add_u64 v[66:67], v[66:67], 0, v[134:135]
	global_load_lds_dwordx4 v[68:69], off
	s_add_i32 m0, s8, 0x4000
	v_lshl_add_u64 v[68:69], v[68:69], 0, v[136:137]
	global_load_lds_dwordx4 v[70:71], off
	v_lshl_add_u64 v[70:71], v[70:71], 0, v[138:139]
	s_cbranch_vccnz .LBB0_490
	s_add_i32 m0, s34, 0x6000
	v_lshl_add_u64 v[150:151], v[72:73], 0, v[140:141]
	global_load_lds_dwordx4 v[72:73], off
	v_mov_b32_e32 v72, v150
	v_mov_b32_e32 v73, v151

.LBB0_493:
	s_and_b64 vcc, exec, s[16:17]
	s_cbranch_vccz .Lmla_slow_nostag
	s_waitcnt vmcnt(0) lgkmcnt(0)
	s_barrier
	s_mov_b64 s[16:17], 0

.Lmla_fast:
	s_and_b32 s8, s30, 3
	s_mulk_i32 s8, 0x6400
	s_add_i32 s8, s8, 0
	v_add3_u32 v142, s8, v144, v145
	v_mul_f32_e32 v253, 0xbe16c740, v148
	s_cmp_lg_u32 s42, 0
	s_cbranch_scc1 .Lmla_fast_havek
	v_add3_u32 v0, s8, v143, v132
	ds_read_b128 v[242:245], v0
	ds_read_b128 v[150:153], v0 offset:32
	ds_read_b128 v[158:161], v0 offset:64
	ds_read_b128 v[162:165], v0 offset:96
	ds_read_b128 v[174:177], v0 offset:128
	ds_read_b128 v[178:181], v0 offset:160
	ds_read_b128 v[246:249], v0 offset:6656
	ds_read_b128 v[154:157], v0 offset:6688
	ds_read_b128 v[166:169], v0 offset:6720
	ds_read_b128 v[170:173], v0 offset:6752
	ds_read_b128 v[194:197], v0 offset:6784
	ds_read_b128 v[198:201], v0 offset:6816
.Lmla_fast_havek:
	s_mov_b32 s42, 0
	s_andn2_b64 vcc, exec, s[38:39]
	s_cbranch_vccnz .Lmla_fast_nodma
	s_add_i32 s34, s30, 2
	s_cmp_gt_u32 s34, s14
	s_cbranch_scc1 .Lmla_fast_d2
	s_and_b32 s8, s34, 2
	s_mulk_i32 s8, 0x6400
	s_add_i32 s34, s8, 0
	s_add_i32 s8, s34, s5
	s_mov_b32 m0, s8
	s_and_b64 vcc, exec, s[36:37]
	global_load_lds_dwordx4 v[66:67], off
	s_add_i32 m0, s8, 0x2000
	v_lshl_add_u64 v[66:67], v[66:67], 0, v[134:135]
	global_load_lds_dwordx4 v[68:69], off
	s_add_i32 m0, s8, 0x4000
	v_lshl_add_u64 v[68:69], v[68:69], 0, v[136:137]
	global_load_lds_dwordx4 v[70:71], off
	v_lshl_add_u64 v[70:71], v[70:71], 0, v[138:139]
	s_cbranch_vccnz .Lmla_fast_d2
	s_add_i32 m0, s34, 0x6000
	v_lshl_add_u64 v[182:183], v[72:73], 0, v[140:141]
	global_load_lds_dwordx4 v[72:73], off
	v_mov_b32_e32 v72, v182
	v_mov_b32_e32 v73, v183
.Lmla_fast_d2:
	s_cmp_gt_u32 s30, s13
	s_cbranch_scc1 .Lmla_fast_nodma
	s_add_i32 s8, s30, -1
	s_and_b32 s8, s8, 3
	s_mulk_i32 s8, 0x6400
	s_add_i32 s34, s8, 0
	s_add_i32 s8, s34, s5
	s_mov_b32 m0, s8
	s_and_b64 vcc, exec, s[36:37]
	global_load_lds_dwordx4 v[66:67], off
	s_add_i32 m0, s8, 0x2000
	v_lshl_add_u64 v[66:67], v[66:67], 0, v[134:135]
	global_load_lds_dwordx4 v[68:69], off
	s_add_i32 m0, s8, 0x4000
	v_lshl_add_u64 v[68:69], v[68:69], 0, v[136:137]
	global_load_lds_dwordx4 v[70:71], off
	v_lshl_add_u64 v[70:71], v[70:71], 0, v[138:139]
	s_cbranch_vccnz .Lmla_fast_nodma
	s_add_i32 m0, s34, 0x6000
	v_lshl_add_u64 v[182:183], v[72:73], 0, v[140:141]
	global_load_lds_dwordx4 v[72:73], off
	v_mov_b32_e32 v72, v182
	v_mov_b32_e32 v73, v183
.Lmla_fast_nodma:
	s_waitcnt lgkmcnt(6)
	v_mfma_f32_32x32x16_bf16 v[50:65], v[242:245], v[74:77], 0
	ds_read_b64_tr_b16 v[126:127], v142 offset:13312
	ds_read_b64_tr_b16 v[128:129], v142 offset:14848
	v_add_f32_e32 v254, v202, v203
	v_add_f32_e32 v255, v204, v205
	v_add_f32_e32 v254, v254, v206
	v_add_f32_e32 v255, v255, v207
	v_add_f32_e32 v254, v254, v208
	v_add_f32_e32 v255, v255, v209
	v_mfma_f32_32x32x16_bf16 v[50:65], v[150:153], v[78:81], v[50:65]
	ds_read_b64_tr_b16 v[124:125], v142 offset:14912
	ds_read_b64_tr_b16 v[122:123], v142 offset:13376
	v_add_f32_e32 v254, v254, v210
	v_add_f32_e32 v255, v255, v211
	v_add_f32_e32 v254, v254, v212
	v_add_f32_e32 v255, v255, v213
	v_add_f32_e32 v254, v254, v214
	v_add_f32_e32 v255, v255, v215
	v_mfma_f32_32x32x16_bf16 v[50:65], v[158:161], v[82:85], v[50:65]
	ds_read_b64_tr_b16 v[118:119], v142 offset:16384
	ds_read_b64_tr_b16 v[120:121], v142 offset:17920
	v_add_f32_e32 v254, v254, v216
	v_add_f32_e32 v255, v255, v217
	v_add_f32_e32 v254, v254, v218
	v_add_f32_e32 v255, v255, v219
	v_add_f32_e32 v254, v254, v220
	v_add_f32_e32 v255, v255, v221
	v_mfma_f32_32x32x16_bf16 v[50:65], v[162:165], v[86:89], v[50:65]
	ds_read_b64_tr_b16 v[116:117], v142 offset:17984
	ds_read_b64_tr_b16 v[114:115], v142 offset:16448
	v_add_f32_e32 v254, v254, v222
	v_add_f32_e32 v255, v255, v223
	v_add_f32_e32 v254, v254, v224
	v_add_f32_e32 v255, v255, v225
	v_add_f32_e32 v254, v254, v226
	v_add_f32_e32 v255, v255, v227
	v_mfma_f32_32x32x16_bf16 v[50:65], v[174:177], v[90:93], v[50:65]
	ds_read_b64_tr_b16 v[110:111], v142 offset:19456
	ds_read_b64_tr_b16 v[112:113], v142 offset:20992
	v_add_f32_e32 v254, v254, v228
	v_add_f32_e32 v255, v255, v229
	v_add_f32_e32 v254, v254, v230
	v_add_f32_e32 v255, v255, v231
	v_add_f32_e32 v254, v254, v232
	v_add_f32_e32 v255, v255, v233
	v_mfma_f32_32x32x16_bf16 v[50:65], v[178:181], v[94:97], v[50:65]
	ds_read_b64_tr_b16 v[108:109], v142 offset:21056
	ds_read_b64_tr_b16 v[106:107], v142 offset:19520
	v_add_f32_e32 v254, v254, v255
	v_add_f32_e32 v147, v147, v254
	s_waitcnt lgkmcnt(12)
	v_mfma_f32_32x32x16_bf16 v[34:49], v[246:249], v[74:77], 0
	ds_read_b64_tr_b16 v[102:103], v142 offset:22528
	ds_read_b64_tr_b16 v[104:105], v142 offset:24064
	v_mfma_f32_32x32x16_bf16 v[34:49], v[154:157], v[78:81], v[34:49]
	ds_read_b64_tr_b16 v[100:101], v142 offset:24128
	ds_read_b64_tr_b16 v[98:99], v142 offset:22592
	s_nop 0
	v_max3_f32 v0, v50, v51, v52
	v_max3_f32 v0, v0, v53, v54
	v_max3_f32 v0, v0, v55, v56
	v_max3_f32 v0, v0, v57, v58
	v_mfma_f32_32x32x16_bf16 v[34:49], v[166:169], v[82:85], v[34:49]
	v_max3_f32 v0, v0, v59, v60
	v_max3_f32 v0, v0, v61, v62
	v_max3_f32 v0, v0, v63, v64
	v_max3_f32 v0, v0, v65, v65
	v_fmamk_f32 v202, v50, 0x3e16c740, v253
	v_exp_f32_e32 v202, v202
	v_mfma_f32_32x32x16_bf16 v[34:49], v[170:173], v[86:89], v[34:49]
	v_fmamk_f32 v203, v51, 0x3e16c740, v253
	v_exp_f32_e32 v203, v203
	v_fmamk_f32 v204, v52, 0x3e16c740, v253
	v_exp_f32_e32 v204, v204
	v_mfma_f32_32x32x16_bf16 v[34:49], v[194:197], v[90:93], v[34:49]
	v_fmamk_f32 v205, v53, 0x3e16c740, v253
	v_exp_f32_e32 v205, v205
	v_fmamk_f32 v206, v54, 0x3e16c740, v253
	v_exp_f32_e32 v206, v206
	v_mfma_f32_32x32x16_bf16 v[34:49], v[198:201], v[94:97], v[34:49]
	s_and_b64 vcc, exec, s[16:17]
	s_cbranch_vccz .Lmla_fast_nostag
	s_waitcnt vmcnt(0) lgkmcnt(0)
	s_barrier
	s_mov_b64 s[16:17], 0
.Lmla_fast_nostag:
	v_fmamk_f32 v207, v55, 0x3e16c740, v253
	v_exp_f32_e32 v207, v207
	v_fmamk_f32 v208, v56, 0x3e16c740, v253
	v_exp_f32_e32 v208, v208
	v_fmamk_f32 v209, v57, 0x3e16c740, v253
	v_exp_f32_e32 v209, v209
	v_fmamk_f32 v210, v58, 0x3e16c740, v253
	v_exp_f32_e32 v210, v210
	v_fmamk_f32 v211, v59, 0x3e16c740, v253
	v_exp_f32_e32 v211, v211
	v_fmamk_f32 v212, v60, 0x3e16c740, v253
	v_exp_f32_e32 v212, v212
	v_fmamk_f32 v213, v61, 0x3e16c740, v253
	v_exp_f32_e32 v213, v213
	v_fmamk_f32 v214, v62, 0x3e16c740, v253
	v_exp_f32_e32 v214, v214
	v_fmamk_f32 v215, v63, 0x3e16c740, v253
	v_exp_f32_e32 v215, v215
	v_fmamk_f32 v216, v64, 0x3e16c740, v253
	v_exp_f32_e32 v216, v216
	v_fmamk_f32 v217, v65, 0x3e16c740, v253
	v_exp_f32_e32 v217, v217
	v_max3_f32 v149, v34, v35, v36
	v_cvt_pk_bf16_f32 v234, v202, v203
	v_max3_f32 v149, v149, v37, v38
	v_cvt_pk_bf16_f32 v235, v204, v205
	v_max3_f32 v149, v149, v39, v40
	v_cvt_pk_bf16_f32 v236, v206, v207
	v_max3_f32 v149, v149, v41, v42
	v_cvt_pk_bf16_f32 v237, v208, v209
	v_max3_f32 v149, v149, v43, v44
	v_cvt_pk_bf16_f32 v238, v210, v211
	v_max3_f32 v149, v149, v45, v46
	v_cvt_pk_bf16_f32 v239, v212, v213
	v_max3_f32 v149, v149, v47, v48
	v_cvt_pk_bf16_f32 v240, v214, v215
	v_max3_f32 v149, v149, v49, v49
	v_cvt_pk_bf16_f32 v241, v216, v217
	v_max_f32_e32 v149, v149, v149
	v_max_f32_e32 v0, v0, v0
	v_max_f32_e32 v0, v0, v149
	v_sub_f32_e32 v149, v0, v148
	v_mul_f32_e32 v149, 0x3e16c740, v149
	v_cmp_lt_f32_e32 vcc, s21, v149
	s_cbranch_vccnz .Lmla_fast_rescale
.Lmla_fast_ok:
	s_waitcnt lgkmcnt(0)
	s_add_i32 s34, s31, 64
	s_cmp_le_u32 s34, s4
	s_cselect_b32 s42, 1, 0
	s_add_i32 s8, s30, 1
	s_and_b32 s8, s8, 3
	s_mulk_i32 s8, 0x6400
	v_add3_u32 v0, s8, v143, v132
	v_mfma_f32_32x32x16_bf16 v[18:33], v[126:129], v[234:237], v[18:33]
	v_fmamk_f32 v218, v34, 0x3e16c740, v253
	v_exp_f32_e32 v218, v218
	v_fmamk_f32 v219, v35, 0x3e16c740, v253
	v_exp_f32_e32 v219, v219
	v_mfma_f32_32x32x16_bf16 v[2:17], v[122:125], v[234:237], v[2:17]
	v_fmamk_f32 v220, v36, 0x3e16c740, v253
	v_exp_f32_e32 v220, v220
	v_fmamk_f32 v221, v37, 0x3e16c740, v253
	v_exp_f32_e32 v221, v221
	v_mfma_f32_32x32x16_bf16 v[18:33], v[118:121], v[238:241], v[18:33]
	v_fmamk_f32 v222, v38, 0x3e16c740, v253
	v_exp_f32_e32 v222, v222
	v_fmamk_f32 v223, v39, 0x3e16c740, v253
	v_exp_f32_e32 v223, v223
	ds_read_b128 v[242:245], v0
	ds_read_b128 v[150:153], v0 offset:32
	v_mfma_f32_32x32x16_bf16 v[2:17], v[114:117], v[238:241], v[2:17]
	v_fmamk_f32 v224, v40, 0x3e16c740, v253
	v_exp_f32_e32 v224, v224
	v_fmamk_f32 v225, v41, 0x3e16c740, v253
	v_exp_f32_e32 v225, v225
	ds_read_b128 v[158:161], v0 offset:64
	ds_read_b128 v[162:165], v0 offset:96
	v_cvt_pk_bf16_f32 v234, v218, v219
	v_cvt_pk_bf16_f32 v235, v220, v221
	v_cvt_pk_bf16_f32 v236, v222, v223
	v_cvt_pk_bf16_f32 v237, v224, v225
	v_fmamk_f32 v226, v42, 0x3e16c740, v253
	v_exp_f32_e32 v226, v226
	v_mfma_f32_32x32x16_bf16 v[18:33], v[110:113], v[234:237], v[18:33]
	v_fmamk_f32 v227, v43, 0x3e16c740, v253
	v_exp_f32_e32 v227, v227
	v_fmamk_f32 v228, v44, 0x3e16c740, v253
	v_exp_f32_e32 v228, v228
	ds_read_b128 v[174:177], v0 offset:128
	ds_read_b128 v[178:181], v0 offset:160
	ds_read_b128 v[246:249], v0 offset:6656
	v_mfma_f32_32x32x16_bf16 v[2:17], v[106:109], v[234:237], v[2:17]
	v_fmamk_f32 v229, v45, 0x3e16c740, v253
	v_exp_f32_e32 v229, v229
	v_fmamk_f32 v230, v46, 0x3e16c740, v253
	v_exp_f32_e32 v230, v230
	ds_read_b128 v[154:157], v0 offset:6688
	ds_read_b128 v[166:169], v0 offset:6720
	ds_read_b128 v[170:173], v0 offset:6752
	v_fmamk_f32 v231, v47, 0x3e16c740, v253
	v_exp_f32_e32 v231, v231
	v_fmamk_f32 v232, v48, 0x3e16c740, v253
	v_exp_f32_e32 v232, v232
	v_fmamk_f32 v233, v49, 0x3e16c740, v253
	v_exp_f32_e32 v233, v233
	v_cvt_pk_bf16_f32 v238, v226, v227
	v_cvt_pk_bf16_f32 v239, v228, v229
	v_cvt_pk_bf16_f32 v240, v230, v231
	v_cvt_pk_bf16_f32 v241, v232, v233
	ds_read_b128 v[194:197], v0 offset:6784
	ds_read_b128 v[198:201], v0 offset:6816
	v_mfma_f32_32x32x16_bf16 v[18:33], v[102:105], v[238:241], v[18:33]
	v_mfma_f32_32x32x16_bf16 v[2:17], v[98:101], v[238:241], v[2:17]
	s_branch .LBB0_498
.Lmla_fast_rescale:
	v_xor_b32_e32 v149, 32, v187
	v_cmp_lt_i32_e32 vcc, v149, v189
	s_nop 1
	v_cndmask_b32_e32 v149, v187, v149, vcc
	v_lshlrev_b32_e32 v149, 2, v149
	ds_bpermute_b32 v149, v149, v0
	s_waitcnt lgkmcnt(0)
	v_max3_f32 v149, v148, v0, v149
	v_sub_f32_e32 v0, v148, v149
	v_mul_f32_e32 v0, 0x3e16c740, v0
	v_exp_f32_e32 v0, v0
	v_mov_b32_e32 v148, v149
	v_pk_mul_f32 v[32:33], v[32:33], v[0:1] op_sel_hi:[1,0]
	v_pk_mul_f32 v[30:31], v[30:31], v[0:1] op_sel_hi:[1,0]
	v_pk_mul_f32 v[28:29], v[28:29], v[0:1] op_sel_hi:[1,0]
	v_pk_mul_f32 v[26:27], v[26:27], v[0:1] op_sel_hi:[1,0]
	v_pk_mul_f32 v[24:25], v[24:25], v[0:1] op_sel_hi:[1,0]
	v_pk_mul_f32 v[22:23], v[22:23], v[0:1] op_sel_hi:[1,0]
	v_pk_mul_f32 v[20:21], v[20:21], v[0:1] op_sel_hi:[1,0]
	v_pk_mul_f32 v[18:19], v[18:19], v[0:1] op_sel_hi:[1,0]
	v_pk_mul_f32 v[16:17], v[16:17], v[0:1] op_sel_hi:[1,0]
	v_pk_mul_f32 v[14:15], v[14:15], v[0:1] op_sel_hi:[1,0]
	v_pk_mul_f32 v[12:13], v[12:13], v[0:1] op_sel_hi:[1,0]
	v_pk_mul_f32 v[10:11], v[10:11], v[0:1] op_sel_hi:[1,0]
	v_pk_mul_f32 v[8:9], v[8:9], v[0:1] op_sel_hi:[1,0]
	v_pk_mul_f32 v[6:7], v[6:7], v[0:1] op_sel_hi:[1,0]
	v_pk_mul_f32 v[4:5], v[4:5], v[0:1] op_sel_hi:[1,0]
	v_pk_mul_f32 v[2:3], v[2:3], v[0:1] op_sel_hi:[1,0]
	v_mul_f32_e32 v147, v147, v0
	v_mul_f32_e32 v253, 0xbe16c740, v148
	v_fmamk_f32 v202, v50, 0x3e16c740, v253
	v_exp_f32_e32 v202, v202
	v_fmamk_f32 v203, v51, 0x3e16c740, v253
	v_exp_f32_e32 v203, v203
	v_fmamk_f32 v204, v52, 0x3e16c740, v253
	v_exp_f32_e32 v204, v204
	v_fmamk_f32 v205, v53, 0x3e16c740, v253
	v_exp_f32_e32 v205, v205
	v_fmamk_f32 v206, v54, 0x3e16c740, v253
	v_exp_f32_e32 v206, v206
	v_fmamk_f32 v207, v55, 0x3e16c740, v253
	v_exp_f32_e32 v207, v207
	v_fmamk_f32 v208, v56, 0x3e16c740, v253
	v_exp_f32_e32 v208, v208
	v_fmamk_f32 v209, v57, 0x3e16c740, v253
	v_exp_f32_e32 v209, v209
	v_fmamk_f32 v210, v58, 0x3e16c740, v253
	v_exp_f32_e32 v210, v210
	v_fmamk_f32 v211, v59, 0x3e16c740, v253
	v_exp_f32_e32 v211, v211
	v_fmamk_f32 v212, v60, 0x3e16c740, v253
	v_exp_f32_e32 v212, v212
	v_fmamk_f32 v213, v61, 0x3e16c740, v253
	v_exp_f32_e32 v213, v213
	v_fmamk_f32 v214, v62, 0x3e16c740, v253
	v_exp_f32_e32 v214, v214
	v_fmamk_f32 v215, v63, 0x3e16c740, v253
	v_exp_f32_e32 v215, v215
	v_fmamk_f32 v216, v64, 0x3e16c740, v253
	v_exp_f32_e32 v216, v216
	v_fmamk_f32 v217, v65, 0x3e16c740, v253
	v_exp_f32_e32 v217, v217
	v_cvt_pk_bf16_f32 v234, v202, v203
	v_cvt_pk_bf16_f32 v235, v204, v205
	v_cvt_pk_bf16_f32 v236, v206, v207
	v_cvt_pk_bf16_f32 v237, v208, v209
	v_cvt_pk_bf16_f32 v238, v210, v211
	v_cvt_pk_bf16_f32 v239, v212, v213
	v_cvt_pk_bf16_f32 v240, v214, v215
	v_cvt_pk_bf16_f32 v241, v216, v217
	s_branch .Lmla_fast_ok

	.amdhsa_kernel _Z9trunk_fwd6Params
		.amdhsa_group_segment_fixed_size 0
		.amdhsa_private_segment_fixed_size 0
		.amdhsa_kernarg_size 400
		.amdhsa_user_sgpr_count 2
		.amdhsa_user_sgpr_dispatch_ptr 0
		.amdhsa_user_sgpr_queue_ptr 0
		.amdhsa_user_sgpr_kernarg_segment_ptr 1
		.amdhsa_user_sgpr_dispatch_id 0
		.amdhsa_user_sgpr_kernarg_preload_length 0
		.amdhsa_user_sgpr_kernarg_preload_offset 0
		.amdhsa_user_sgpr_private_segment_size 0
		.amdhsa_uses_dynamic_stack 0
		.amdhsa_enable_private_segment 0
		.amdhsa_system_sgpr_workgroup_id_x 1
		.amdhsa_system_sgpr_workgroup_id_y 0
		.amdhsa_system_sgpr_workgroup_id_z 0
		.amdhsa_system_sgpr_workgroup_info 0
		.amdhsa_system_vgpr_workitem_id 2
		.amdhsa_next_free_vgpr 256
		.amdhsa_next_free_sgpr 100
		.amdhsa_accum_offset 256
		.amdhsa_reserve_vcc 1
		.amdhsa_float_round_mode_32 0
		.amdhsa_float_round_mode_16_64 0
		.amdhsa_float_denorm_mode_32 3
		.amdhsa_float_denorm_mode_16_64 3
		.amdhsa_dx10_clamp 1
		.amdhsa_ieee_mode 1
		.amdhsa_fp16_overflow 0
		.amdhsa_tg_split 0
		.amdhsa_exception_fp_ieee_invalid_op 0
		.amdhsa_exception_fp_denorm_src 0
		.amdhsa_exception_fp_ieee_div_zero 0
		.amdhsa_exception_fp_ieee_overflow 0
		.amdhsa_exception_fp_ieee_underflow 0
		.amdhsa_exception_fp_ieee_inexact 0
		.amdhsa_exception_int_div_zero 0
	.end_amdhsa_kernel

.Lfunc_end0:
	.size	_Z9trunk_fwd6Params, .Lfunc_end0-_Z9trunk_fwd6Params
	.set _Z9trunk_fwd6Params.num_vgpr, 256
	.set _Z9trunk_fwd6Params.num_agpr, 0
	.set _Z9trunk_fwd6Params.numbered_sgpr, 100
	.set _Z9trunk_fwd6Params.num_named_barrier, 0
	.set _Z9trunk_fwd6Params.private_seg_size, 0
	.set _Z9trunk_fwd6Params.uses_vcc, 1
	.set _Z9trunk_fwd6Params.uses_flat_scratch, 0
	.set _Z9trunk_fwd6Params.has_dyn_sized_stack, 0
	.set _Z9trunk_fwd6Params.has_recursion, 0
	.set _Z9trunk_fwd6Params.has_indirect_call, 0

amdhsa.kernels:
  - .agpr_count:     0
    .args:
      - .offset:         0
        .size:           144
        .value_kind:     by_value
      - .offset:         144
        .size:           4
        .value_kind:     hidden_block_count_x
      - .offset:         148
        .size:           4
        .value_kind:     hidden_block_count_y
      - .offset:         152
        .size:           4
        .value_kind:     hidden_block_count_z
      - .offset:         156
        .size:           2
        .value_kind:     hidden_group_size_x
      - .offset:         158
        .size:           2
        .value_kind:     hidden_group_size_y
      - .offset:         160
        .size:           2
        .value_kind:     hidden_group_size_z
      - .offset:         162
        .size:           2
        .value_kind:     hidden_remainder_x
      - .offset:         164
        .size:           2
        .value_kind:     hidden_remainder_y
      - .offset:         166
        .size:           2
        .value_kind:     hidden_remainder_z
      - .offset:         184
        .size:           8
        .value_kind:     hidden_global_offset_x
      - .offset:         192
        .size:           8
        .value_kind:     hidden_global_offset_y
      - .offset:         200
        .size:           8
        .value_kind:     hidden_global_offset_z
      - .offset:         208
        .size:           2
        .value_kind:     hidden_grid_dims
      - .offset:         232
        .size:           8
        .value_kind:     hidden_multigrid_sync_arg
      - .offset:         264
        .size:           4
        .value_kind:     hidden_dynamic_lds_size
    .group_segment_fixed_size: 0
    .kernarg_segment_align: 8
    .kernarg_segment_size: 400
    .language:       OpenCL C
    .language_version:
      - 2
      - 0
    .max_flat_workgroup_size: 512
    .name:           _Z9trunk_fwd6Params
    .private_segment_fixed_size: 0
    .sgpr_count:     106
    .sgpr_spill_count: 187
    .symbol:         _Z9trunk_fwd6Params.kd
    .uniform_work_group_size: 1
    .uses_dynamic_stack: false
    .vgpr_count:     256
    .vgpr_spill_count: 0
    .wavefront_size: 64
